# v24
# speedup vs baseline: 1.0160x; 1.0160x over previous
; DEVI void attn_unit(const Params& p, char* lds, int au) {
;     ...
;     float lmx[2];
; #pragma unroll
;     for (int qb = 0; qb < 2; ++qb) {
;       float m2 = fmaxf(fmaxf(sc[0][qb][0], sc[0][qb][1]), fmaxf(sc[0][qb][2], sc[0][qb][3]));
; #pragma unroll
;       for (int kb = 1; kb < 4; ++kb)
;         m2 = fmaxf(m2, fmaxf(fmaxf(sc[kb][qb][0], sc[kb][qb][1]), fmaxf(sc[kb][qb][2], sc[kb][qb][3])));
;       lmx[qb] = m2;
;     }
;     const bool first = (i == 0);
;     if (__any(first || (i == 1 && ((lmx[0] > 0.f) || (lmx[1] > 0.f))) || (lmx[0] > 6.f) || (lmx[1] > 6.f))) {
; #pragma unroll
;       for (int qb = 0; qb < 2; ++qb) {
;         float m2 = lmx[qb];
;         m2 = fmaxf(m2, __shfl_xor(m2, 16));
;         m2 = fmaxf(m2, __shfl_xor(m2, 32));
;         const float d = first ? m2 : fmaxf(m2, 0.f);
;         const float alpha = first ? 0.f : __builtin_amdgcn_exp2f(-d);
;         mrun[qb] += d;
;         lsum[qb] *= alpha;
; #pragma unroll
;         for (int db = 0; db < 8; ++db) o[db][qb] *= alpha;
; #pragma unroll
;         for (int kb = 0; kb < 4; ++kb) sc[kb][qb] -= d;
;       }
;     }
.LBB0_215:
	s_or_b64 exec, exec, s[2:3]
	v_max3_f32 v147, v90, v91, v92
	v_max3_f32 v146, v110, v111, v112
	v_max3_f32 v147, v147, v93, v118
	v_max3_f32 v146, v146, v113, v106
	v_max3_f32 v147, v147, v119, v120
	v_max3_f32 v146, v146, v107, v108
	v_max3_f32 v147, v147, v121, v98
	v_max3_f32 v146, v146, v109, v102
	v_max3_f32 v147, v147, v99, v100
	v_max3_f32 v146, v146, v103, v104
	v_max3_f32 v147, v147, v101, v114
	v_max3_f32 v146, v146, v105, v94
	v_max3_f32 v147, v147, v115, v116
	v_max3_f32 v146, v146, v95, v96
	v_max_f32_e32 v147, v147, v117
	v_max_f32_e32 v146, v146, v97
	v_max_f32_e32 v148, v146, v147
	s_mov_b32 s2, 0x40c00000
	v_cmp_lt_f32_e32 vcc, s2, v148
	s_cbranch_vccz .LBB0_217
	ds_bpermute_b32 v148, v123, v147
	v_max_f32_e32 v147, v147, v147
	s_waitcnt lgkmcnt(0)
	v_max_f32_e32 v148, v148, v148
	v_max_f32_e32 v147, v147, v148
	ds_bpermute_b32 v148, v125, v147
	s_waitcnt lgkmcnt(0)
	v_max3_f32 v147, v147, v148, 0
	v_exp_f32_e64 v148, -v147
	v_sub_f32_e32 v90, v90, v147
	v_sub_f32_e32 v91, v91, v147
	v_sub_f32_e32 v92, v92, v147
	v_pk_mul_f32 v[138:139], v[138:139], v[148:149] op_sel_hi:[1,0]
	v_pk_mul_f32 v[136:137], v[136:137], v[148:149] op_sel_hi:[1,0]
	v_pk_mul_f32 v[84:85], v[84:85], v[148:149] op_sel_hi:[1,0]
	v_pk_mul_f32 v[82:83], v[82:83], v[148:149] op_sel_hi:[1,0]
	v_pk_mul_f32 v[76:77], v[76:77], v[148:149] op_sel_hi:[1,0]
	v_pk_mul_f32 v[74:75], v[74:75], v[148:149] op_sel_hi:[1,0]
	v_pk_mul_f32 v[68:69], v[68:69], v[148:149] op_sel_hi:[1,0]
	v_pk_mul_f32 v[66:67], v[66:67], v[148:149] op_sel_hi:[1,0]
	v_pk_mul_f32 v[56:57], v[56:57], v[148:149] op_sel_hi:[1,0]
	v_pk_mul_f32 v[54:55], v[54:55], v[148:149] op_sel_hi:[1,0]
	v_pk_mul_f32 v[48:49], v[48:49], v[148:149] op_sel_hi:[1,0]
	v_pk_mul_f32 v[46:47], v[46:47], v[148:149] op_sel_hi:[1,0]
	v_pk_mul_f32 v[40:41], v[40:41], v[148:149] op_sel_hi:[1,0]
	v_pk_mul_f32 v[38:39], v[38:39], v[148:149] op_sel_hi:[1,0]
	v_pk_mul_f32 v[32:33], v[32:33], v[148:149] op_sel_hi:[1,0]
	v_pk_mul_f32 v[30:31], v[30:31], v[148:149] op_sel_hi:[1,0]
	v_pk_mul_f32 v[24:25], v[24:25], v[148:149] op_sel_hi:[1,0]
	v_pk_mul_f32 v[22:23], v[22:23], v[148:149] op_sel_hi:[1,0]
	ds_bpermute_b32 v148, v123, v146
	v_max_f32_e32 v146, v146, v146
	v_sub_f32_e32 v93, v93, v147
	v_sub_f32_e32 v118, v118, v147
	v_sub_f32_e32 v119, v119, v147
	s_waitcnt lgkmcnt(0)
	v_max_f32_e32 v148, v148, v148
	v_max_f32_e32 v146, v146, v148
	ds_bpermute_b32 v148, v125, v146
	v_sub_f32_e32 v120, v120, v147
	v_sub_f32_e32 v121, v121, v147
	v_sub_f32_e32 v98, v98, v147
	v_sub_f32_e32 v99, v99, v147
	s_waitcnt lgkmcnt(0)
	v_max3_f32 v146, v146, v148, 0
	v_exp_f32_e64 v148, -v146
	v_sub_f32_e32 v100, v100, v147
	v_sub_f32_e32 v101, v101, v147
	v_sub_f32_e32 v114, v114, v147
	v_sub_f32_e32 v115, v115, v147
	v_sub_f32_e32 v116, v116, v147
	v_sub_f32_e32 v117, v117, v147
	v_pk_add_f32 v[134:135], v[134:135], v[146:147]
	v_pk_mul_f32 v[142:143], v[142:143], v[148:149] op_sel_hi:[1,0]
	v_pk_mul_f32 v[140:141], v[140:141], v[148:149] op_sel_hi:[1,0]
	v_pk_mul_f32 v[80:81], v[80:81], v[148:149] op_sel_hi:[1,0]
	v_pk_mul_f32 v[78:79], v[78:79], v[148:149] op_sel_hi:[1,0]
	v_pk_mul_f32 v[72:73], v[72:73], v[148:149] op_sel_hi:[1,0]
	v_pk_mul_f32 v[70:71], v[70:71], v[148:149] op_sel_hi:[1,0]
	v_pk_mul_f32 v[60:61], v[60:61], v[148:149] op_sel_hi:[1,0]
	v_pk_mul_f32 v[58:59], v[58:59], v[148:149] op_sel_hi:[1,0]
	v_pk_mul_f32 v[52:53], v[52:53], v[148:149] op_sel_hi:[1,0]
	v_pk_mul_f32 v[50:51], v[50:51], v[148:149] op_sel_hi:[1,0]
	v_pk_mul_f32 v[44:45], v[44:45], v[148:149] op_sel_hi:[1,0]
	v_pk_mul_f32 v[42:43], v[42:43], v[148:149] op_sel_hi:[1,0]
	v_pk_mul_f32 v[36:37], v[36:37], v[148:149] op_sel_hi:[1,0]
	v_pk_mul_f32 v[34:35], v[34:35], v[148:149] op_sel_hi:[1,0]
	v_pk_mul_f32 v[28:29], v[28:29], v[148:149] op_sel_hi:[1,0]
	v_pk_mul_f32 v[26:27], v[26:27], v[148:149] op_sel_hi:[1,0]
	v_pk_mul_f32 v[4:5], v[4:5], v[148:149] op_sel_hi:[1,0]
	v_pk_mul_f32 v[2:3], v[2:3], v[148:149] op_sel_hi:[1,0]
	v_sub_f32_e32 v110, v110, v146
	v_sub_f32_e32 v111, v111, v146
	v_sub_f32_e32 v112, v112, v146
	v_sub_f32_e32 v113, v113, v146
	v_sub_f32_e32 v106, v106, v146
	v_sub_f32_e32 v107, v107, v146
	v_sub_f32_e32 v108, v108, v146
	v_sub_f32_e32 v109, v109, v146
	v_sub_f32_e32 v102, v102, v146
	v_sub_f32_e32 v103, v103, v146
	v_sub_f32_e32 v104, v104, v146
	v_sub_f32_e32 v105, v105, v146
	v_sub_f32_e32 v94, v94, v146
	v_sub_f32_e32 v95, v95, v146
	v_sub_f32_e32 v96, v96, v146
	v_sub_f32_e32 v97, v97, v146
